# grid barriers after the channel-DFT and FFT phases: no L2 writeback by the XCC leader (every store of those phases is write-through)
# speedup vs baseline: 1.0234x; 1.0020x over previous
; __device__ __forceinline__ unsigned xb_ld(unsigned* p)              { return __hip_atomic_load(p, __ATOMIC_RELAXED, __HIP_MEMORY_SCOPE_AGENT); }
; __device__ __forceinline__ unsigned xb_add(unsigned* p, unsigned v) { return __hip_atomic_fetch_add(p, v, __ATOMIC_RELAXED, __HIP_MEMORY_SCOPE_AGENT); }
; #define XB_SPIN(cond, bar) do { unsigned _sp = 0; while (cond) { __builtin_amdgcn_s_sleep(1); \
;     if ((++_sp & 255u) == 0u) { if (xb_ld(&(bar)[XB_TMO])) break; if (_sp > XB_SPIN_CAP) { atomicAdd(&(bar)[XB_TMO], 1u); break; } } } } while (0)
; __device__ __forceinline__ void xcd_barrier(const XcdBarrier& b) {
;     asm volatile("s_waitcnt vmcnt(0)" ::: "memory");
;     __syncthreads();
;     if (threadIdx.x == 0) {
;         unsigned* bar = b.bar;
;         __builtin_amdgcn_s_waitcnt(0);
;         unsigned nloc = b.st[0], nx = b.st[1];
;         if (nloc == 0u) { xcd_barrier_complete(bar, b.x, nloc, nx); b.st[0] = nloc; b.st[1] = nx; }
;         const unsigned old = xb_add(&bar[XB_XSUB(b.x)], 1u);
;         const unsigned gen = old / nloc;
;         if (old + 1u == (gen + 1u) * nloc) {
;             __builtin_amdgcn_fence(__ATOMIC_RELEASE, "agent");
;             asm volatile("s_waitcnt vmcnt(0)" ::: "memory");
;             const unsigned og = xb_add(&bar[XB_TOP], 1u);
;             const unsigned tg = og / nx;
;             if (og + 1u == (tg + 1u) * nx) xb_add(&bar[XB_TOPGEN], 1u);
;             else XB_SPIN(xb_ld(&bar[XB_TOPGEN]) == tg, bar);
;             __builtin_amdgcn_fence(__ATOMIC_ACQUIRE, "agent");
;             xb_add(&bar[XB_XGEN(b.x)], 1u);
;             asm volatile("s_waitcnt vmcnt(0)" ::: "memory");
.LBB0_136:
	v_readlane_b32 s0, v254, 51
	s_add_i32 s0, s0, 2
	s_cmp_ge_i32 s0, s57
	s_cbranch_scc1 .LBB0_190
	s_waitcnt vmcnt(0)
	s_waitcnt vmcnt(0) lgkmcnt(0)
	s_barrier
	s_mov_b64 s[4:5], exec
	v_readlane_b32 s2, v252, 11
	v_readlane_b32 s3, v252, 12
	s_and_b64 s[2:3], s[4:5], s[2:3]
	s_mov_b64 exec, s[2:3]
	s_cbranch_execz .Lgb1_done
	v_mov_b32_e32 v2, 0x22160
	v_mov_b32_e32 v3, 1
	ds_read2_b32 v[4:5], v2 offset1:1
	ds_add_rtn_u32 v6, v2, v3 offset:8
	v_readlane_b32 s10, v253, 52
	v_readlane_b32 s11, v253, 53
	s_add_u32 s10, s10, 0xc000
	s_addc_u32 s11, s11, 0
	s_getreg_b32 s9, hwreg(HW_REG_XCC_ID, 0, 4)
	s_lshl_b32 s9, s9, 8
	s_add_u32 s12, s10, s9
	s_addc_u32 s13, s11, 0
	v_mov_b32_e32 v2, 0
	global_atomic_add v7, v2, v3, s[12:13] offset:1024 sc0
	s_waitcnt lgkmcnt(0)
	v_readfirstlane_b32 s14, v4
	v_readfirstlane_b32 s15, v5
	v_readfirstlane_b32 s8, v6
	s_add_u32 s8, s8, 1
	s_mul_i32 s14, s14, s8
	s_mul_i32 s15, s15, s8
	s_waitcnt vmcnt(0)
	v_readfirstlane_b32 s9, v7
	s_add_u32 s9, s9, 1
	s_cmp_lg_u32 s9, s14
	s_cbranch_scc1 .Lgb1_nonleader
	buffer_inv sc1
	global_atomic_add v2, v3, s[10:11]
	s_branch .Lgb1_poll

; __device__ __forceinline__ unsigned xb_ld(unsigned* p)              { return __hip_atomic_load(p, __ATOMIC_RELAXED, __HIP_MEMORY_SCOPE_AGENT); }
; __device__ __forceinline__ unsigned xb_add(unsigned* p, unsigned v) { return __hip_atomic_fetch_add(p, v, __ATOMIC_RELAXED, __HIP_MEMORY_SCOPE_AGENT); }
; #define XB_SPIN(cond, bar) do { unsigned _sp = 0; while (cond) { __builtin_amdgcn_s_sleep(1); \
;     if ((++_sp & 255u) == 0u) { if (xb_ld(&(bar)[XB_TMO])) break; if (_sp > XB_SPIN_CAP) { atomicAdd(&(bar)[XB_TMO], 1u); break; } } } } while (0)
; __device__ __forceinline__ void xcd_barrier(const XcdBarrier& b) {
;     asm volatile("s_waitcnt vmcnt(0)" ::: "memory");
;     __syncthreads();
;     if (threadIdx.x == 0) {
;         unsigned* bar = b.bar;
;         __builtin_amdgcn_s_waitcnt(0);
;         unsigned nloc = b.st[0], nx = b.st[1];
;         if (nloc == 0u) { xcd_barrier_complete(bar, b.x, nloc, nx); b.st[0] = nloc; b.st[1] = nx; }
;         const unsigned old = xb_add(&bar[XB_XSUB(b.x)], 1u);
;         const unsigned gen = old / nloc;
;         if (old + 1u == (gen + 1u) * nloc) {
;             __builtin_amdgcn_fence(__ATOMIC_RELEASE, "agent");
;             asm volatile("s_waitcnt vmcnt(0)" ::: "memory");
;             const unsigned og = xb_add(&bar[XB_TOP], 1u);
;             const unsigned tg = og / nx;
;             if (og + 1u == (tg + 1u) * nx) xb_add(&bar[XB_TOPGEN], 1u);
;             else XB_SPIN(xb_ld(&bar[XB_TOPGEN]) == tg, bar);
;             __builtin_amdgcn_fence(__ATOMIC_ACQUIRE, "agent");
;             xb_add(&bar[XB_XGEN(b.x)], 1u);
;             asm volatile("s_waitcnt vmcnt(0)" ::: "memory");
.LBB0_218:
	v_readlane_b32 s0, v254, 51
	s_add_i32 s0, s0, 4
	s_cmp_ge_i32 s0, s57
	s_mov_b64 s[8:9], 0
	s_cbranch_scc1 .LBB0_272
	s_waitcnt vmcnt(0)
	s_waitcnt vmcnt(0) lgkmcnt(0)
	s_barrier
	s_mov_b64 s[4:5], exec
	v_readlane_b32 s2, v252, 11
	v_readlane_b32 s3, v252, 12
	s_and_b64 s[2:3], s[4:5], s[2:3]
	s_mov_b64 exec, s[2:3]
	s_cbranch_execz .Lgb2_done
	v_mov_b32_e32 v2, 0x22160
	v_mov_b32_e32 v3, 1
	ds_read2_b32 v[4:5], v2 offset1:1
	ds_add_rtn_u32 v6, v2, v3 offset:8
	v_readlane_b32 s10, v253, 52
	v_readlane_b32 s11, v253, 53
	s_add_u32 s10, s10, 0xc000
	s_addc_u32 s11, s11, 0
	s_getreg_b32 s9, hwreg(HW_REG_XCC_ID, 0, 4)
	s_lshl_b32 s9, s9, 8
	s_add_u32 s12, s10, s9
	s_addc_u32 s13, s11, 0
	v_mov_b32_e32 v2, 0
	global_atomic_add v7, v2, v3, s[12:13] offset:1024 sc0
	s_waitcnt lgkmcnt(0)
	v_readfirstlane_b32 s14, v4
	v_readfirstlane_b32 s15, v5
	v_readfirstlane_b32 s8, v6
	s_add_u32 s8, s8, 1
	s_mul_i32 s14, s14, s8
	s_mul_i32 s15, s15, s8
	s_waitcnt vmcnt(0)
	v_readfirstlane_b32 s9, v7
	s_add_u32 s9, s9, 1
	s_cmp_lg_u32 s9, s14
	s_cbranch_scc1 .Lgb2_nonleader
	buffer_inv sc1
	global_atomic_add v2, v3, s[10:11]
	s_branch .Lgb2_poll
